# completion-counter polls of phases 5 / 6 issued ahead of the first epilogue's loads and checked after their first wait
# baseline (speedup 1.0000x reference)
;     __device__ __forceinline__ void operator()(const f32x4 (&acc)[2][2][4][2], const pg8::Unit& u, int wr, int wc, int fr, int fq) const {
;         u32x4 xr[2][4][2];
; #pragma unroll
;         for (int ai = 0; ai < 2; ++ai)
; #pragma unroll
;             for (int m = 0; m < 4; ++m)
; #pragma unroll
;                 for (int bj = 0; bj < 2; ++bj)
;                     xr[ai][m][bj] = *(const u32x4*)(xb + (size_t)(u.pm * 256 + ai * 128 + wr * 64 + m * 16 + fr) * DM + u.pn * 256 + 128 * bj + 32 * wc + 8 * fq);
;         __builtin_amdgcn_sched_barrier(0);
.LBB0_938:
	s_cmp_eq_u32 s98, 1
	s_cbranch_scc1 .Lx_ok
	v_mov_b32_e32 v252, 0
	global_load_dword v252, v252, s[100:101] sc1
.Lx_ok:
	s_lshl_b32 s9, s34, 8
	s_lshl_b32 s34, s8, 8
	v_add_u32_e32 v120, s9, v185
	s_ashr_i32 s35, s34, 31
	s_lshl_b64 s[36:37], s[34:35], 1
	v_ashrrev_i32_e32 v121, 31, v120
	v_or_b32_e32 v230, 16, v120
	v_lshl_add_u64 v[122:123], v[196:197], 0, s[36:37]
	v_lshlrev_b64 v[250:251], 11, v[120:121]
	v_ashrrev_i32_e32 v231, 31, v230
	v_or_b32_e32 v226, 32, v120
	v_lshl_add_u64 v[124:125], v[122:123], 0, v[250:251]
	v_lshlrev_b64 v[232:233], 11, v[230:231]
	v_ashrrev_i32_e32 v227, 31, v226
	v_or_b32_e32 v222, 48, v120
	global_load_dwordx4 v[242:245], v[124:125], off nt
	global_load_dwordx4 v[246:249], v[124:125], off offset:256 nt
	v_lshl_add_u64 v[124:125], v[122:123], 0, v[232:233]
	v_lshlrev_b64 v[228:229], 11, v[226:227]
	v_ashrrev_i32_e32 v223, 31, v222
	v_add_u32_e32 v218, 0x80, v120
	global_load_dwordx4 v[180:183], v[124:125], off nt
	global_load_dwordx4 v[176:179], v[124:125], off offset:256 nt
	v_lshl_add_u64 v[124:125], v[122:123], 0, v[228:229]
	v_lshlrev_b64 v[224:225], 11, v[222:223]
	v_ashrrev_i32_e32 v219, 31, v218
	v_add_u32_e32 v214, 0x90, v120
	global_load_dwordx4 v[172:175], v[124:125], off nt
	global_load_dwordx4 v[168:171], v[124:125], off offset:256 nt
	v_lshl_add_u64 v[124:125], v[122:123], 0, v[224:225]
	v_lshlrev_b64 v[220:221], 11, v[218:219]
	v_ashrrev_i32_e32 v215, 31, v214
	v_add_u32_e32 v210, 0xa0, v120
	v_add_u32_e32 v206, 0xb0, v120
	global_load_dwordx4 v[164:167], v[124:125], off nt
	global_load_dwordx4 v[160:163], v[124:125], off offset:256 nt
	v_lshl_add_u64 v[124:125], v[122:123], 0, v[220:221]
	v_lshlrev_b64 v[216:217], 11, v[214:215]
	v_ashrrev_i32_e32 v211, 31, v210
	v_ashrrev_i32_e32 v207, 31, v206
	global_load_dwordx4 v[156:159], v[124:125], off nt
	global_load_dwordx4 v[152:155], v[124:125], off offset:256 nt
	v_lshl_add_u64 v[124:125], v[122:123], 0, v[216:217]
	v_lshlrev_b64 v[212:213], 11, v[210:211]
	v_lshlrev_b64 v[208:209], 11, v[206:207]
	global_load_dwordx4 v[148:151], v[124:125], off nt
	global_load_dwordx4 v[144:147], v[124:125], off offset:256 nt
	v_lshl_add_u64 v[124:125], v[122:123], 0, v[212:213]
	v_lshl_add_u64 v[120:121], v[122:123], 0, v[208:209]
	global_load_dwordx4 v[140:143], v[124:125], off nt
	global_load_dwordx4 v[136:139], v[124:125], off offset:256 nt
	s_nop 0
	global_load_dwordx4 v[124:127], v[120:121], off nt
	s_nop 0
	global_load_dwordx4 v[120:123], v[120:121], off offset:256 nt
	s_waitcnt vmcnt(15)
	s_cmp_eq_u32 s98, 1
	s_cbranch_scc1 .Lx_go
.Lx_chk:
	v_readfirstlane_b32 s99, v252
	s_cmp_ge_u32 s99, s88
	s_cbranch_scc1 .Lx_set
	s_sleep 1
	v_mov_b32_e32 v252, 0
	global_load_dword v252, v252, s[100:101] sc1
	s_waitcnt vmcnt(0)
	s_branch .Lx_chk

;     __device__ __forceinline__ void operator()(const f32x4 (&acc)[2][2][4][2], const pg8::Unit& u, int wr, int wc, int fr, int fq) const {
;     ...
;         for (int ai = 0; ai < 2; ++ai)
; #pragma unroll
;             for (int m = 0; m < 4; ++m) {
;                 const int row = u.pm * 256 + ai * 128 + wr * 64 + m * 16 + fr;
;                 float ss = 0.f;
; #pragma unroll
;                 for (int bj = 0; bj < 2; ++bj) {
;                     const size_t off = (size_t)row * DM + u.pn * 256 + 128 * bj + 32 * wc + 8 * fq;
;                     const u32x4 w = xr[ai][m][bj];
;                     float y[8];
;                     y[0] = __uint_as_float(w.x << 16) + acc[ai][bj][m][0].x; y[1] = __uint_as_float(w.x & 0xffff0000u) + acc[ai][bj][m][0].y;
;                     y[2] = __uint_as_float(w.y << 16) + acc[ai][bj][m][0].z; y[3] = __uint_as_float(w.y & 0xffff0000u) + acc[ai][bj][m][0].w;
;                     y[4] = __uint_as_float(w.z << 16) + acc[ai][bj][m][1].x; y[5] = __uint_as_float(w.z & 0xffff0000u) + acc[ai][bj][m][1].y;
;                     y[6] = __uint_as_float(w.w << 16) + acc[ai][bj][m][1].z; y[7] = __uint_as_float(w.w & 0xffff0000u) + acc[ai][bj][m][1].w;
;                     store8(x2b + off, y);
; #pragma unroll
;                     for (int i = 0; i < 8; ++i) ss += y[i] * y[i];
;                 }
;                 ss += __shfl_xor(ss, 16); ss += __shfl_xor(ss, 32);
;                 if (fq == 0) red[wc * 256 + (row & 255)] = ss;
.Lx_go:
	v_lshlrev_b32_e32 v207, 16, v242
	v_add_f32_e32 v207, v132, v207
	v_and_b32_e32 v132, 0xffff0000, v242
	v_add_f32_e32 v211, v133, v132
	v_lshlrev_b32_e32 v132, 16, v243
	v_add_f32_e32 v134, v134, v132
	v_and_b32_e32 v132, 0xffff0000, v243
	v_add_f32_e32 v135, v135, v132
	v_lshlrev_b32_e32 v132, 16, v244
	v_add_f32_e32 v215, v128, v132
	v_and_b32_e32 v128, 0xffff0000, v244
	v_add_f32_e32 v219, v129, v128
	v_lshlrev_b32_e32 v128, 16, v245
	v_add_f32_e32 v223, v130, v128
	v_and_b32_e32 v128, 0xffff0000, v245
	v_add_f32_e32 v131, v131, v128
	v_lshl_add_u64 v[128:129], s[16:17], 0, v[250:251]
	v_lshl_add_u64 v[128:129], v[128:129], 0, s[36:37]
	v_lshl_add_u64 v[128:129], v[128:129], 0, s[10:11]
	v_lshl_add_u64 v[132:133], v[128:129], 0, v[194:195]
	v_cvt_pk_bf16_f32 v128, v207, v211
	v_mul_f32_e32 v211, v211, v211
	v_fmac_f32_e32 v211, v207, v207
	v_fmac_f32_e32 v211, v134, v134
	v_fmac_f32_e32 v211, v135, v135
	v_fmac_f32_e32 v211, v215, v215
	s_waitcnt vmcnt(14)
	v_lshlrev_b32_e32 v130, 16, v246
	v_fmac_f32_e32 v211, v219, v219
	v_add_f32_e32 v116, v116, v130
	v_and_b32_e32 v130, 0xffff0000, v246
	v_fmac_f32_e32 v211, v223, v223
	v_add_f32_e32 v117, v117, v130
	v_lshlrev_b32_e32 v130, 16, v247
	v_fmac_f32_e32 v211, v131, v131
	v_add_f32_e32 v118, v118, v130
	v_and_b32_e32 v130, 0xffff0000, v247
	v_add_f32_e32 v119, v119, v130
	v_lshlrev_b32_e32 v130, 16, v248
	v_fmac_f32_e32 v211, v116, v116
	v_cvt_pk_bf16_f32 v129, v134, v135
	v_add_f32_e32 v134, v112, v130
	v_and_b32_e32 v112, 0xffff0000, v248
	v_fmac_f32_e32 v211, v117, v117
	v_add_f32_e32 v135, v113, v112
	v_lshlrev_b32_e32 v112, 16, v249
	v_fmac_f32_e32 v211, v118, v118
	v_add_f32_e32 v207, v114, v112
	v_and_b32_e32 v112, 0xffff0000, v249
	v_fmac_f32_e32 v211, v119, v119
	v_and_b32_e32 v113, 64, v240
	v_add_f32_e32 v227, v115, v112
	v_fmac_f32_e32 v211, v134, v134
	v_xor_b32_e32 v112, 16, v240
	v_add_u32_e32 v113, 64, v113
	v_fmac_f32_e32 v211, v135, v135
	v_cmp_lt_i32_e32 vcc, v112, v113
	v_fmac_f32_e32 v211, v207, v207
	v_fmac_f32_e32 v211, v227, v227
	v_cndmask_b32_e32 v112, v240, v112, vcc
	v_lshlrev_b32_e32 v112, 2, v112
	ds_bpermute_b32 v114, v112, v211
	v_xor_b32_e32 v115, 32, v240
	v_cmp_lt_i32_e32 vcc, v115, v113
	v_cvt_pk_bf16_f32 v130, v215, v219
	v_cvt_pk_bf16_f32 v131, v223, v131
	s_waitcnt lgkmcnt(0)
	v_add_f32_e32 v114, v211, v114
	global_store_dwordx4 v[132:133], v[128:131], off
	v_cndmask_b32_e32 v113, v240, v115, vcc
	v_lshlrev_b32_e32 v113, 2, v113
	ds_bpermute_b32 v115, v113, v114
	v_cvt_pk_bf16_f32 v116, v116, v117
	v_cvt_pk_bf16_f32 v117, v118, v119
	v_cvt_pk_bf16_f32 v118, v134, v135
	v_cvt_pk_bf16_f32 v119, v207, v227
	global_store_dwordx4 v[132:133], v[116:119], off offset:256
	s_and_saveexec_b64 s[36:37], s[2:3]
	s_cbranch_execz .LBB0_940
	s_waitcnt lgkmcnt(0)
	v_add_f32_e32 v114, v114, v115
	ds_write_b32 v235, v114

;     __device__ __forceinline__ void operator()(const f32x4 (&acc)[2][2][4][2], const pg8::Unit& u, int wr, int wc, int fr, int fq) const {
;         f32x4 sq[2][4];
; #pragma unroll
;         for (int ai = 0; ai < 2; ++ai)
; #pragma unroll
;             for (int m = 0; m < 4; ++m) sq[ai][m] = *(const f32x4*)(ssqp + (size_t)(u.pm * 256 + ai * 128 + wr * 64 + m * 16 + fr) * 4);
;         __builtin_amdgcn_sched_barrier(0);
.LBB0_1010:
	s_cmp_eq_u32 s98, 1
	s_cbranch_scc1 .Lh_ok
	v_mov_b32_e32 v219, 0
	global_load_dword v219, v219, s[100:101] sc1

;     __device__ __forceinline__ void operator()(const f32x4 (&acc)[2][2][4][2], const pg8::Unit& u, int wr, int wc, int fr, int fq) const {
;         f32x4 sq[2][4];
; #pragma unroll
;         for (int ai = 0; ai < 2; ++ai)
; #pragma unroll
;             for (int m = 0; m < 4; ++m) sq[ai][m] = *(const f32x4*)(ssqp + (size_t)(u.pm * 256 + ai * 128 + wr * 64 + m * 16 + fr) * 4);
;         __builtin_amdgcn_sched_barrier(0);
.Lh_chk:
	v_readfirstlane_b32 s99, v219
	s_cmp_ge_u32 s99, s88
	s_cbranch_scc1 .Lh_set
	s_sleep 1
	v_mov_b32_e32 v219, 0
	global_load_dword v219, v219, s[100:101] sc1
	s_waitcnt vmcnt(0)
	s_branch .Lh_chk
.Lh_set:
	s_mov_b32 s98, 1
.Lr6_join:
	s_xor_b32 s84, s84, 0x1000
	s_mov_b32 s85, 1
	s_cmp_lg_u64 s[2:3], 0
	s_cbranch_scc0 .Lr6_nodma
	v_readfirstlane_b32 s82, v184
	s_lshr_b32 s82, s82, 6
	s_cmp_gt_u32 s82, 3
	s_cbranch_scc1 .Lr6_nodma
	s_lshl_b32 s83, s24, 8
	s_lshl_b32 s81, s82, 6
	s_add_i32 s83, s83, s81
	v_and_b32_e32 v218, 63, v184
	v_add_u32_e32 v218, s83, v218
	v_lshlrev_b32_e32 v218, 4, v218
	s_lshl_b32 s82, s82, 10
	s_add_i32 s82, s82, s84
	s_add_i32 m0, s82, 0x20000
	s_nop 1
	global_load_lds_dwordx4 v218, s[8:9]
